# G3 epilogue stage 2 hand-scheduled: 8 row-stat loads and 12 vector loads up front instead of one per row group; same arithmetic
# speedup vs baseline: 1.0124x; 1.0124x over previous
.LBB0_574:
	s_or_b64 exec, exec, s[52:53]
	s_add_u32 s48, s74, s43
	s_addc_u32 s49, s75, s41
	s_waitcnt lgkmcnt(0)
	v_lshlrev_b64 v[228:229], 2, v[156:157]
	v_lshl_add_u64 v[206:207], v[158:159], 2, s[20:21]
	v_lshl_add_u64 v[230:231], s[48:49], 0, v[228:229]
	s_add_u32 s48, s76, s43
	s_addc_u32 s49, s77, s41
	v_lshl_add_u64 v[232:233], s[50:51], 0, v[228:229]
	v_lshl_add_u64 v[204:205], s[48:49], 0, v[228:229]
	global_load_dword v186, v[206:207], off offset:0 sc1
	global_load_dword v187, v[206:207], off offset:64 sc1
	global_load_dword v188, v[206:207], off offset:128 sc1
	global_load_dword v189, v[206:207], off offset:192 sc1
	global_load_dword v190, v[206:207], off offset:512 sc1
	global_load_dword v191, v[206:207], off offset:576 sc1
	global_load_dword v192, v[206:207], off offset:640 sc1
	global_load_dword v193, v[206:207], off offset:704 sc1
	global_load_dwordx4 v[162:165], v[230:231], off offset:0
	global_load_dwordx4 v[166:169], v[230:231], off offset:64
	global_load_dwordx4 v[170:173], v[230:231], off offset:512
	global_load_dwordx4 v[174:177], v[230:231], off offset:576
	global_load_dwordx4 v[212:215], v[232:233], off offset:0
	global_load_dwordx4 v[216:219], v[232:233], off offset:64
	global_load_dwordx4 v[220:223], v[232:233], off offset:512
	global_load_dwordx4 v[224:227], v[232:233], off offset:576
	global_load_dwordx4 v[8:11], v[204:205], off offset:0
	global_load_dwordx4 v[0:3], v[204:205], off offset:64
	global_load_dwordx4 v[12:15], v[204:205], off offset:512
	global_load_dwordx4 v[4:7], v[204:205], off offset:576
	v_lshlrev_b64 v[228:229], 1, v[156:157]
	v_lshlrev_b64 v[194:195], 11, v[158:159]
	v_lshl_add_u64 v[194:195], s[28:29], 0, v[194:195]
	v_lshl_add_u64 v[194:195], v[194:195], 0, v[228:229]
	s_andn2_b64 vcc, exec, s[8:9]
	s_mov_b64 s[8:9], -1
	s_mov_b32 s101, 0
	s_waitcnt vmcnt(4)
	v_pk_add_f32 v[162:163], v[162:163], 1.0 op_sel_hi:[1,0]
	v_pk_add_f32 v[164:165], v[164:165], 1.0 op_sel_hi:[1,0]
	v_pk_add_f32 v[166:167], v[166:167], 1.0 op_sel_hi:[1,0]
	v_pk_add_f32 v[168:169], v[168:169], 1.0 op_sel_hi:[1,0]
	v_pk_add_f32 v[170:171], v[170:171], 1.0 op_sel_hi:[1,0]
	v_pk_add_f32 v[172:173], v[172:173], 1.0 op_sel_hi:[1,0]
	v_pk_add_f32 v[174:175], v[174:175], 1.0 op_sel_hi:[1,0]
	v_pk_add_f32 v[176:177], v[176:177], 1.0 op_sel_hi:[1,0]
	v_pk_mul_f32 v[162:163], v[212:213], v[162:163]
	v_pk_mul_f32 v[164:165], v[214:215], v[164:165]
	v_pk_mul_f32 v[166:167], v[216:217], v[166:167]
	v_pk_mul_f32 v[168:169], v[218:219], v[168:169]
	v_pk_mul_f32 v[170:171], v[220:221], v[170:171]
	v_pk_mul_f32 v[172:173], v[222:223], v[172:173]
	v_pk_mul_f32 v[174:175], v[224:225], v[174:175]
	v_pk_mul_f32 v[176:177], v[226:227], v[176:177]
	s_waitcnt vmcnt(0)
	v_fmamk_f32 v178, v186, 0x3a800000, v202
	v_rsq_f32_e32 v178, v178
	s_nop 0
	v_pk_mul_f32 v[140:141], v[140:141], v[178:179] op_sel_hi:[1,0]
	v_pk_mul_f32 v[142:143], v[142:143], v[178:179] op_sel_hi:[1,0]
	v_pk_mul_f32 v[136:137], v[136:137], v[178:179] op_sel_hi:[1,0]
	v_pk_mul_f32 v[138:139], v[138:139], v[178:179] op_sel_hi:[1,0]
	v_pk_mul_f32 v[132:133], v[132:133], v[178:179] op_sel_hi:[1,0]
	v_pk_mul_f32 v[134:135], v[134:135], v[178:179] op_sel_hi:[1,0]
	v_pk_mul_f32 v[160:161], v[160:161], v[178:179] op_sel_hi:[1,0]
	v_pk_mul_f32 v[130:131], v[130:131], v[178:179] op_sel_hi:[1,0]
	v_pk_fma_f32 v[140:141], v[162:163], v[140:141], v[8:9]
	v_pk_fma_f32 v[142:143], v[164:165], v[142:143], v[10:11]
	v_pk_fma_f32 v[136:137], v[166:167], v[136:137], v[0:1]
	v_pk_fma_f32 v[138:139], v[168:169], v[138:139], v[2:3]
	v_pk_fma_f32 v[132:133], v[170:171], v[132:133], v[12:13]
	v_pk_fma_f32 v[134:135], v[172:173], v[134:135], v[14:15]
	v_pk_fma_f32 v[160:161], v[174:175], v[160:161], v[4:5]
	v_pk_fma_f32 v[130:131], v[176:177], v[130:131], v[6:7]
	v_cvt_pk_bf16_f32 v140, v140, v141
	v_cvt_pk_bf16_f32 v141, v142, v143
	global_store_dwordx2 v[194:195], v[140:141], off offset:0
	v_cvt_pk_bf16_f32 v136, v136, v137
	v_cvt_pk_bf16_f32 v137, v138, v139
	global_store_dwordx2 v[194:195], v[136:137], off offset:32
	v_cvt_pk_bf16_f32 v132, v132, v133
	v_cvt_pk_bf16_f32 v133, v134, v135
	global_store_dwordx2 v[194:195], v[132:133], off offset:256
	v_cvt_pk_bf16_f32 v160, v160, v161
	v_cvt_pk_bf16_f32 v161, v130, v131
	global_store_dwordx2 v[194:195], v[160:161], off offset:288
	v_fmamk_f32 v178, v187, 0x3a800000, v202
	v_rsq_f32_e32 v178, v178
	s_mov_b32 s100, 0x8000
	v_lshl_add_u64 v[184:185], v[194:195], 0, s[100:101]
	v_pk_mul_f32 v[124:125], v[124:125], v[178:179] op_sel_hi:[1,0]
	v_pk_mul_f32 v[126:127], v[126:127], v[178:179] op_sel_hi:[1,0]
	v_pk_mul_f32 v[120:121], v[120:121], v[178:179] op_sel_hi:[1,0]
	v_pk_mul_f32 v[122:123], v[122:123], v[178:179] op_sel_hi:[1,0]
	v_pk_mul_f32 v[104:105], v[104:105], v[178:179] op_sel_hi:[1,0]
	v_pk_mul_f32 v[106:107], v[106:107], v[178:179] op_sel_hi:[1,0]
	v_pk_mul_f32 v[96:97], v[96:97], v[178:179] op_sel_hi:[1,0]
	v_pk_mul_f32 v[98:99], v[98:99], v[178:179] op_sel_hi:[1,0]
	v_pk_fma_f32 v[124:125], v[162:163], v[124:125], v[8:9]
	v_pk_fma_f32 v[126:127], v[164:165], v[126:127], v[10:11]
	v_pk_fma_f32 v[120:121], v[166:167], v[120:121], v[0:1]
	v_pk_fma_f32 v[122:123], v[168:169], v[122:123], v[2:3]
	v_pk_fma_f32 v[104:105], v[170:171], v[104:105], v[12:13]
	v_pk_fma_f32 v[106:107], v[172:173], v[106:107], v[14:15]
	v_pk_fma_f32 v[96:97], v[174:175], v[96:97], v[4:5]
	v_pk_fma_f32 v[98:99], v[176:177], v[98:99], v[6:7]
	v_cvt_pk_bf16_f32 v124, v124, v125
	v_cvt_pk_bf16_f32 v125, v126, v127
	global_store_dwordx2 v[184:185], v[124:125], off offset:0
	v_cvt_pk_bf16_f32 v120, v120, v121
	v_cvt_pk_bf16_f32 v121, v122, v123
	global_store_dwordx2 v[184:185], v[120:121], off offset:32
	v_cvt_pk_bf16_f32 v104, v104, v105
	v_cvt_pk_bf16_f32 v105, v106, v107
	global_store_dwordx2 v[184:185], v[104:105], off offset:256
	v_cvt_pk_bf16_f32 v96, v96, v97
	v_cvt_pk_bf16_f32 v97, v98, v99
	global_store_dwordx2 v[184:185], v[96:97], off offset:288
	v_fmamk_f32 v178, v188, 0x3a800000, v202
	v_rsq_f32_e32 v178, v178
	s_mov_b32 s100, 0x10000
	v_lshl_add_u64 v[184:185], v[194:195], 0, s[100:101]
	v_pk_mul_f32 v[92:93], v[92:93], v[178:179] op_sel_hi:[1,0]
	v_pk_mul_f32 v[94:95], v[94:95], v[178:179] op_sel_hi:[1,0]
	v_pk_mul_f32 v[88:89], v[88:89], v[178:179] op_sel_hi:[1,0]
	v_pk_mul_f32 v[90:91], v[90:91], v[178:179] op_sel_hi:[1,0]
	v_pk_mul_f32 v[84:85], v[84:85], v[178:179] op_sel_hi:[1,0]
	v_pk_mul_f32 v[86:87], v[86:87], v[178:179] op_sel_hi:[1,0]
	v_pk_mul_f32 v[80:81], v[80:81], v[178:179] op_sel_hi:[1,0]
	v_pk_mul_f32 v[82:83], v[82:83], v[178:179] op_sel_hi:[1,0]
	v_pk_fma_f32 v[92:93], v[162:163], v[92:93], v[8:9]
	v_pk_fma_f32 v[94:95], v[164:165], v[94:95], v[10:11]
	v_pk_fma_f32 v[88:89], v[166:167], v[88:89], v[0:1]
	v_pk_fma_f32 v[90:91], v[168:169], v[90:91], v[2:3]
	v_pk_fma_f32 v[84:85], v[170:171], v[84:85], v[12:13]
	v_pk_fma_f32 v[86:87], v[172:173], v[86:87], v[14:15]
	v_pk_fma_f32 v[80:81], v[174:175], v[80:81], v[4:5]
	v_pk_fma_f32 v[82:83], v[176:177], v[82:83], v[6:7]
	v_cvt_pk_bf16_f32 v92, v92, v93
	v_cvt_pk_bf16_f32 v93, v94, v95
	global_store_dwordx2 v[184:185], v[92:93], off offset:0
	v_cvt_pk_bf16_f32 v88, v88, v89
	v_cvt_pk_bf16_f32 v89, v90, v91
	global_store_dwordx2 v[184:185], v[88:89], off offset:32
	v_cvt_pk_bf16_f32 v84, v84, v85
	v_cvt_pk_bf16_f32 v85, v86, v87
	global_store_dwordx2 v[184:185], v[84:85], off offset:256
	v_cvt_pk_bf16_f32 v80, v80, v81
	v_cvt_pk_bf16_f32 v81, v82, v83
	global_store_dwordx2 v[184:185], v[80:81], off offset:288
	v_fmamk_f32 v178, v189, 0x3a800000, v202
	v_rsq_f32_e32 v178, v178
	s_mov_b32 s100, 0x18000
	v_lshl_add_u64 v[184:185], v[194:195], 0, s[100:101]
	v_pk_mul_f32 v[76:77], v[76:77], v[178:179] op_sel_hi:[1,0]
	v_pk_mul_f32 v[78:79], v[78:79], v[178:179] op_sel_hi:[1,0]
	v_pk_mul_f32 v[72:73], v[72:73], v[178:179] op_sel_hi:[1,0]
	v_pk_mul_f32 v[74:75], v[74:75], v[178:179] op_sel_hi:[1,0]
	v_pk_mul_f32 v[68:69], v[68:69], v[178:179] op_sel_hi:[1,0]
	v_pk_mul_f32 v[70:71], v[70:71], v[178:179] op_sel_hi:[1,0]
	v_pk_mul_f32 v[64:65], v[64:65], v[178:179] op_sel_hi:[1,0]
	v_pk_mul_f32 v[66:67], v[66:67], v[178:179] op_sel_hi:[1,0]
	v_pk_fma_f32 v[76:77], v[162:163], v[76:77], v[8:9]
	v_pk_fma_f32 v[78:79], v[164:165], v[78:79], v[10:11]
	v_pk_fma_f32 v[72:73], v[166:167], v[72:73], v[0:1]
	v_pk_fma_f32 v[74:75], v[168:169], v[74:75], v[2:3]
	v_pk_fma_f32 v[68:69], v[170:171], v[68:69], v[12:13]
	v_pk_fma_f32 v[70:71], v[172:173], v[70:71], v[14:15]
	v_pk_fma_f32 v[64:65], v[174:175], v[64:65], v[4:5]
	v_pk_fma_f32 v[66:67], v[176:177], v[66:67], v[6:7]
	v_cvt_pk_bf16_f32 v76, v76, v77
	v_cvt_pk_bf16_f32 v77, v78, v79
	global_store_dwordx2 v[184:185], v[76:77], off offset:0
	v_cvt_pk_bf16_f32 v72, v72, v73
	v_cvt_pk_bf16_f32 v73, v74, v75
	global_store_dwordx2 v[184:185], v[72:73], off offset:32
	v_cvt_pk_bf16_f32 v68, v68, v69
	v_cvt_pk_bf16_f32 v69, v70, v71
	global_store_dwordx2 v[184:185], v[68:69], off offset:256
	v_cvt_pk_bf16_f32 v64, v64, v65
	v_cvt_pk_bf16_f32 v65, v66, v67
	global_store_dwordx2 v[184:185], v[64:65], off offset:288
	v_fmamk_f32 v178, v190, 0x3a800000, v202
	v_rsq_f32_e32 v178, v178
	s_mov_b32 s100, 0x40000
	v_lshl_add_u64 v[184:185], v[194:195], 0, s[100:101]
	v_pk_mul_f32 v[60:61], v[60:61], v[178:179] op_sel_hi:[1,0]
	v_pk_mul_f32 v[62:63], v[62:63], v[178:179] op_sel_hi:[1,0]
	v_pk_mul_f32 v[56:57], v[56:57], v[178:179] op_sel_hi:[1,0]
	v_pk_mul_f32 v[58:59], v[58:59], v[178:179] op_sel_hi:[1,0]
	v_pk_mul_f32 v[52:53], v[52:53], v[178:179] op_sel_hi:[1,0]
	v_pk_mul_f32 v[54:55], v[54:55], v[178:179] op_sel_hi:[1,0]
	v_pk_mul_f32 v[48:49], v[48:49], v[178:179] op_sel_hi:[1,0]
	v_pk_mul_f32 v[50:51], v[50:51], v[178:179] op_sel_hi:[1,0]
	v_pk_fma_f32 v[60:61], v[162:163], v[60:61], v[8:9]
	v_pk_fma_f32 v[62:63], v[164:165], v[62:63], v[10:11]
	v_pk_fma_f32 v[56:57], v[166:167], v[56:57], v[0:1]
	v_pk_fma_f32 v[58:59], v[168:169], v[58:59], v[2:3]
	v_pk_fma_f32 v[52:53], v[170:171], v[52:53], v[12:13]
	v_pk_fma_f32 v[54:55], v[172:173], v[54:55], v[14:15]
	v_pk_fma_f32 v[48:49], v[174:175], v[48:49], v[4:5]
	v_pk_fma_f32 v[50:51], v[176:177], v[50:51], v[6:7]
	v_cvt_pk_bf16_f32 v60, v60, v61
	v_cvt_pk_bf16_f32 v61, v62, v63
	global_store_dwordx2 v[184:185], v[60:61], off offset:0
	v_cvt_pk_bf16_f32 v56, v56, v57
	v_cvt_pk_bf16_f32 v57, v58, v59
	global_store_dwordx2 v[184:185], v[56:57], off offset:32
	v_cvt_pk_bf16_f32 v52, v52, v53
	v_cvt_pk_bf16_f32 v53, v54, v55
	global_store_dwordx2 v[184:185], v[52:53], off offset:256
	v_cvt_pk_bf16_f32 v48, v48, v49
	v_cvt_pk_bf16_f32 v49, v50, v51
	global_store_dwordx2 v[184:185], v[48:49], off offset:288
	v_fmamk_f32 v178, v191, 0x3a800000, v202
	v_rsq_f32_e32 v178, v178
	s_mov_b32 s100, 0x48000
	v_lshl_add_u64 v[184:185], v[194:195], 0, s[100:101]
	v_pk_mul_f32 v[44:45], v[44:45], v[178:179] op_sel_hi:[1,0]
	v_pk_mul_f32 v[46:47], v[46:47], v[178:179] op_sel_hi:[1,0]
	v_pk_mul_f32 v[40:41], v[40:41], v[178:179] op_sel_hi:[1,0]
	v_pk_mul_f32 v[42:43], v[42:43], v[178:179] op_sel_hi:[1,0]
	v_pk_mul_f32 v[36:37], v[36:37], v[178:179] op_sel_hi:[1,0]
	v_pk_mul_f32 v[38:39], v[38:39], v[178:179] op_sel_hi:[1,0]
	v_pk_mul_f32 v[32:33], v[32:33], v[178:179] op_sel_hi:[1,0]
	v_pk_mul_f32 v[34:35], v[34:35], v[178:179] op_sel_hi:[1,0]
	v_pk_fma_f32 v[44:45], v[162:163], v[44:45], v[8:9]
	v_pk_fma_f32 v[46:47], v[164:165], v[46:47], v[10:11]
	v_pk_fma_f32 v[40:41], v[166:167], v[40:41], v[0:1]
	v_pk_fma_f32 v[42:43], v[168:169], v[42:43], v[2:3]
	v_pk_fma_f32 v[36:37], v[170:171], v[36:37], v[12:13]
	v_pk_fma_f32 v[38:39], v[172:173], v[38:39], v[14:15]
	v_pk_fma_f32 v[32:33], v[174:175], v[32:33], v[4:5]
	v_pk_fma_f32 v[34:35], v[176:177], v[34:35], v[6:7]
	v_cvt_pk_bf16_f32 v44, v44, v45
	v_cvt_pk_bf16_f32 v45, v46, v47
	global_store_dwordx2 v[184:185], v[44:45], off offset:0
	v_cvt_pk_bf16_f32 v40, v40, v41
	v_cvt_pk_bf16_f32 v41, v42, v43
	global_store_dwordx2 v[184:185], v[40:41], off offset:32
	v_cvt_pk_bf16_f32 v36, v36, v37
	v_cvt_pk_bf16_f32 v37, v38, v39
	global_store_dwordx2 v[184:185], v[36:37], off offset:256
	v_cvt_pk_bf16_f32 v32, v32, v33
	v_cvt_pk_bf16_f32 v33, v34, v35
	global_store_dwordx2 v[184:185], v[32:33], off offset:288
	v_fmamk_f32 v178, v192, 0x3a800000, v202
	v_rsq_f32_e32 v178, v178
	s_mov_b32 s100, 0x50000
	v_lshl_add_u64 v[184:185], v[194:195], 0, s[100:101]
	v_pk_mul_f32 v[28:29], v[28:29], v[178:179] op_sel_hi:[1,0]
	v_pk_mul_f32 v[30:31], v[30:31], v[178:179] op_sel_hi:[1,0]
	v_pk_mul_f32 v[24:25], v[24:25], v[178:179] op_sel_hi:[1,0]
	v_pk_mul_f32 v[26:27], v[26:27], v[178:179] op_sel_hi:[1,0]
	v_pk_mul_f32 v[20:21], v[20:21], v[178:179] op_sel_hi:[1,0]
	v_pk_mul_f32 v[22:23], v[22:23], v[178:179] op_sel_hi:[1,0]
	v_pk_mul_f32 v[182:183], v[182:183], v[178:179] op_sel_hi:[1,0]
	v_pk_mul_f32 v[180:181], v[180:181], v[178:179] op_sel_hi:[1,0]
	v_pk_fma_f32 v[28:29], v[162:163], v[28:29], v[8:9]
	v_pk_fma_f32 v[30:31], v[164:165], v[30:31], v[10:11]
	v_pk_fma_f32 v[24:25], v[166:167], v[24:25], v[0:1]
	v_pk_fma_f32 v[26:27], v[168:169], v[26:27], v[2:3]
	v_pk_fma_f32 v[20:21], v[170:171], v[20:21], v[12:13]
	v_pk_fma_f32 v[22:23], v[172:173], v[22:23], v[14:15]
	v_pk_fma_f32 v[182:183], v[174:175], v[182:183], v[4:5]
	v_pk_fma_f32 v[180:181], v[176:177], v[180:181], v[6:7]
	v_cvt_pk_bf16_f32 v28, v28, v29
	v_cvt_pk_bf16_f32 v29, v30, v31
	global_store_dwordx2 v[184:185], v[28:29], off offset:0
	v_cvt_pk_bf16_f32 v24, v24, v25
	v_cvt_pk_bf16_f32 v25, v26, v27
	global_store_dwordx2 v[184:185], v[24:25], off offset:32
	v_cvt_pk_bf16_f32 v20, v20, v21
	v_cvt_pk_bf16_f32 v21, v22, v23
	global_store_dwordx2 v[184:185], v[20:21], off offset:256
	v_cvt_pk_bf16_f32 v182, v182, v183
	v_cvt_pk_bf16_f32 v183, v180, v181
	global_store_dwordx2 v[184:185], v[182:183], off offset:288
	v_fmamk_f32 v178, v193, 0x3a800000, v202
	v_rsq_f32_e32 v178, v178
	s_mov_b32 s100, 0x58000
	v_lshl_add_u64 v[184:185], v[194:195], 0, s[100:101]
	v_pk_mul_f32 v[18:19], v[18:19], v[178:179] op_sel_hi:[1,0]
	v_pk_mul_f32 v[16:17], v[16:17], v[178:179] op_sel_hi:[1,0]
	v_pk_mul_f32 v[112:113], v[112:113], v[178:179] op_sel_hi:[1,0]
	v_pk_mul_f32 v[114:115], v[114:115], v[178:179] op_sel_hi:[1,0]
	v_pk_mul_f32 v[108:109], v[108:109], v[178:179] op_sel_hi:[1,0]
	v_pk_mul_f32 v[110:111], v[110:111], v[178:179] op_sel_hi:[1,0]
	v_pk_mul_f32 v[100:101], v[100:101], v[178:179] op_sel_hi:[1,0]
	v_pk_mul_f32 v[102:103], v[102:103], v[178:179] op_sel_hi:[1,0]
	v_pk_fma_f32 v[18:19], v[162:163], v[18:19], v[8:9]
	v_pk_fma_f32 v[16:17], v[164:165], v[16:17], v[10:11]
	v_pk_fma_f32 v[112:113], v[166:167], v[112:113], v[0:1]
	v_pk_fma_f32 v[114:115], v[168:169], v[114:115], v[2:3]
	v_pk_fma_f32 v[108:109], v[170:171], v[108:109], v[12:13]
	v_pk_fma_f32 v[110:111], v[172:173], v[110:111], v[14:15]
	v_pk_fma_f32 v[100:101], v[174:175], v[100:101], v[4:5]
	v_pk_fma_f32 v[102:103], v[176:177], v[102:103], v[6:7]
	v_cvt_pk_bf16_f32 v18, v18, v19
	v_cvt_pk_bf16_f32 v19, v16, v17
	global_store_dwordx2 v[184:185], v[18:19], off offset:0
	v_cvt_pk_bf16_f32 v112, v112, v113
	v_cvt_pk_bf16_f32 v113, v114, v115
	global_store_dwordx2 v[184:185], v[112:113], off offset:32
	v_cvt_pk_bf16_f32 v108, v108, v109
	v_cvt_pk_bf16_f32 v109, v110, v111
	global_store_dwordx2 v[184:185], v[108:109], off offset:256
	v_cvt_pk_bf16_f32 v100, v100, v101
	v_cvt_pk_bf16_f32 v101, v102, v103
	global_store_dwordx2 v[184:185], v[100:101], off offset:288
	s_cbranch_vccnz .LBB0_536
	s_andn2_b64 vcc, exec, s[0:1]
	s_cbranch_vccnz .LBB0_535
	s_barrier
	s_branch .LBB0_535
